# group barriers skip the L2 writeback when all 4 members report the same XCC id (per-group census at entry)
# speedup vs baseline: 1.0656x; 1.0208x over previous
; #define LAS __attribute__((address_space(3)))
; __device__ __forceinline__ CArgs* kargs() { CArgs* p = (CArgs*)__builtin_amdgcn_kernarg_segment_ptr(); asm volatile("" : "+s"(p)); return p; }
; __device__ __forceinline__ unsigned xb_add(unsigned* p, unsigned v) { return __hip_atomic_fetch_add(p, v, __ATOMIC_RELAXED, __HIP_MEMORY_SCOPE_AGENT); }
; __device__ __forceinline__ unsigned xb_xcc_id() { return (unsigned)__builtin_amdgcn_s_getreg((3 << 11) | 20) & 0xFu; }
; __device__ __forceinline__ XcdBarrier xcd_barrier_post(unsigned* bar, volatile LAS unsigned* st) {
;     XcdBarrier b; b.bar = bar; b.x = xb_xcc_id(); b.st = st;
;     if (threadIdx.x == 0) (void)xb_add(&bar[XB_XCNT(b.x)], 1u);
;     return b;
; __global__ void __launch_bounds__(512, 2) fwd_megakernel(Args a) {
;     extern __shared__ __attribute__((aligned(16))) unsigned char lds_raw[];
;     LAS unsigned char* lds = (LAS unsigned char*)lds_raw;
;     cg::grid_group grid = cg::this_grid();
;     const int panel = blockIdx.x;
;     if (threadIdx.x < 2) ((LAS unsigned*)(lds + LDS_XB))[threadIdx.x] = 0u;
;     __syncthreads();
;     const XcdBarrier xbar = xcd_barrier_post((unsigned*)kargs()->ws, (volatile LAS unsigned*)(lds + LDS_XB));
_Z14fwd_megakernel4Args:
	s_load_dwordx2 s[20:21], s[0:1], 0x100
	s_add_u32 s22, s0, 0x100
	v_and_b32_e32 v189, 0x3ff, v0
	v_writelane_b32 v249, s0, 0
	s_addc_u32 s23, s1, 0
	v_cmp_gt_u32_e32 vcc, 2, v189
	v_writelane_b32 v249, s1, 1
	s_and_saveexec_b64 s[4:5], vcc
	v_lshl_add_u32 v1, v189, 2, 0
	v_add_u32_e32 v1, 0x22000, v1
	v_mov_b32_e32 v2, 0
	ds_write_b32 v1, v2
	s_or_b64 exec, exec, s[4:5]
	v_readlane_b32 s0, v249, 0
	v_readlane_b32 s1, v249, 1
	s_waitcnt lgkmcnt(0)
	s_barrier
	s_load_dwordx2 s[80:81], s[0:1], 0xf8
	s_getreg_b32 s0, hwreg(HW_REG_XCC_ID, 0, 4)
	s_and_b32 s0, s0, 15
	v_cmp_eq_u32_e64 s[6:7], 0, v189
	s_mov_b64 s[4:5], exec
	s_nop 0
	v_writelane_b32 v249, s6, 2
	s_nop 1
	v_writelane_b32 v249, s7, 3
	s_and_b64 s[6:7], s[4:5], s[6:7]
	s_mov_b64 exec, s[6:7]
	s_cbranch_execz .LBB0_5
	s_mov_b64 s[6:7], exec
	v_mbcnt_lo_u32_b32 v1, s6, 0
	v_mbcnt_hi_u32_b32 v1, s7, v1
	v_cmp_eq_u32_e32 vcc, 0, v1
	s_and_b64 s[8:9], exec, vcc
	s_mov_b64 exec, s[8:9]
	s_cbranch_execz .LBB0_5
	s_lshl_b32 s1, s0, 8
	s_bcnt1_i32_b64 s3, s[6:7]
	v_mov_b32_e32 v1, s1
	v_mov_b32_e32 v2, s3
	s_waitcnt lgkmcnt(0)
	global_atomic_add v1, v2, s[80:81] offset:1024
	s_lshr_b32 s1, s2, 3
	s_and_b32 s1, s1, 3
	s_lshl_b32 s1, s1, 3
	s_add_u32 s3, s0, 1
	s_lshl_b32 s3, s3, s1
	s_and_b32 s8, s2, 7
	s_lshr_b32 s9, s2, 5
	s_lshl_b32 s9, s9, 3
	s_or_b32 s8, s8, s9
	s_lshl_b32 s8, s8, 2
	s_add_u32 s8, s8, 0x3600
	v_mov_b32_e32 v1, s8
	v_mov_b32_e32 v2, s3
	global_atomic_add v1, v2, s[80:81]

; __device__ __forceinline__ CArgs* kargs() { CArgs* p = (CArgs*)__builtin_amdgcn_kernarg_segment_ptr(); asm volatile("" : "+s"(p)); return p; }
; __global__ void __launch_bounds__(512, 2) fwd_megakernel(Args a) {
;     ...
;     prologue(*kargs(), lds, panel, (int)gridDim.x);
;     grid.sync();
.LBB0_118:
	s_or_b64 exec, exec, s[4:5]
	v_readlane_b32 s4, v249, 0
	v_readlane_b32 s5, v249, 1
	s_barrier
; __device__ __forceinline__ CArgs* kargs() { CArgs* p = (CArgs*)__builtin_amdgcn_kernarg_segment_ptr(); asm volatile("" : "+s"(p)); return p; }
; #define PHASE_PTRS() CArgs* ka = kargs(); unsigned char* ws = ka->ws; unsigned char* PB = ws + WS_PANEL + (size_t)panel * PANEL_BYTES; \
;         bf16_t* HBp = (bf16_t*)(ws + WS_HB) + (size_t)panel * 256 * DM; float* Hp = ka->out + (size_t)panel * 256 * DM; (void)PB; (void)HBp; (void)Hp
; __global__ void __launch_bounds__(512, 2) fwd_megakernel(Args a) {
;     ...
;     for (int l = 0; l < NLAYER; ++l) {
;         gz_phase(*kargs(), l, panel);
;         {
;             PHASE_PTRS();
;             pg8::Gemm g{HBp, (const bf16_t*)(ws + WS_WIN) + (size_t)l * DINP * DM, DM}; pg8::PanelOrder S{NZ_MAIN / 256};
;             pg8::EpiBf16<0> E{(bf16_t*)(PB + P_Z), DINP};
	s_and_b32 s98, s2, 7
	s_lshr_b32 s99, s2, 5
	s_lshl_b32 s99, s99, 3
	s_or_b32 s98, s98, s99
	s_lshl_b32 s98, s98, 2
	s_add_u32 s98, s98, 0x3600
	v_mov_b32_e32 v2, s98
	global_load_dword v0, v2, s[80:81] sc1
	s_waitcnt vmcnt(0)
	v_readfirstlane_b32 s98, v0
	s_nop 3
	s_lshr_b32 s99, s98, 8
	s_lshl_b32 s100, s98, 24
	s_or_b32 s99, s99, s100
	s_cmp_eq_u32 s99, s98
	s_cselect_b32 s98, 1, 0
	s_nop 0
	v_writelane_b32 v248, s98, 62
	s_load_dword s4, s[4:5], 0x108
	s_mul_i32 s1, s21, s20
	s_lshl_b64 s[88:89], s[2:3], 21
	v_and_b32_e32 v0, 0x70, v1
	v_add_u32_e32 v2, -1, v1
	s_waitcnt lgkmcnt(0)
	s_mul_i32 s1, s1, s4
	s_add_u32 s4, s80, 0x200
	v_writelane_b32 v249, s1, 10
	s_addc_u32 s5, s81, 0
	v_writelane_b32 v249, s4, 11
	v_cmp_lt_i32_e32 vcc, v2, v0
	s_mov_b32 s34, 0x3f317218
	v_writelane_b32 v249, s5, 12
	s_add_u32 s4, s80, 0x1000
	s_addc_u32 s5, s81, 0
	v_writelane_b32 v249, s4, 13
	v_cndmask_b32_e32 v2, v2, v1, vcc
	v_lshlrev_b32_e32 v223, 2, v2
	v_writelane_b32 v249, s5, 14
	s_add_u32 s4, s80, 0x1100
	s_addc_u32 s5, s81, 0
	v_writelane_b32 v249, s4, 15
	v_add_u32_e32 v2, -2, v1
	v_cmp_lt_i32_e32 vcc, v2, v0
	v_writelane_b32 v249, s5, 16
	s_add_u32 s4, s80, 0x1200
	s_addc_u32 s5, s81, 0
	v_writelane_b32 v249, s4, 17
	v_cndmask_b32_e32 v2, v2, v1, vcc
	v_lshlrev_b32_e32 v224, 2, v2
	v_writelane_b32 v249, s5, 18
	s_add_u32 s4, s80, 0x1300
	s_addc_u32 s5, s81, 0
	v_writelane_b32 v249, s4, 19
	s_cmp_eq_u32 s0, 15
	v_add_u32_e32 v2, -4, v1
	v_writelane_b32 v249, s5, 20
	s_cselect_b64 s[4:5], -1, 0
	v_writelane_b32 v249, s4, 21
	s_cmp_eq_u32 s0, 14
	v_cmp_lt_i32_e32 vcc, v2, v0
	v_writelane_b32 v249, s5, 22
	s_cselect_b64 s[4:5], -1, 0
	v_writelane_b32 v249, s4, 23
	s_cmp_eq_u32 s0, 13
	v_cndmask_b32_e32 v2, v2, v1, vcc
	v_writelane_b32 v249, s5, 24
	s_cselect_b64 s[4:5], -1, 0
	v_writelane_b32 v249, s4, 25
	s_cmp_eq_u32 s0, 12
	v_lshlrev_b32_e32 v225, 2, v2
	v_writelane_b32 v249, s5, 26
	s_cselect_b64 s[4:5], -1, 0
	v_writelane_b32 v249, s4, 27
	s_cmp_eq_u32 s0, 11
	v_add_u32_e32 v2, -8, v1
	v_writelane_b32 v249, s5, 28
	s_cselect_b64 s[4:5], -1, 0
	v_writelane_b32 v249, s4, 29
	s_cmp_eq_u32 s0, 10
	v_cmp_lt_i32_e32 vcc, v2, v0
	v_writelane_b32 v249, s5, 30
	s_cselect_b64 s[4:5], -1, 0
	v_writelane_b32 v249, s4, 31
	s_cmp_eq_u32 s0, 9
	v_cndmask_b32_e32 v0, v2, v1, vcc
	v_writelane_b32 v249, s5, 32
	s_cselect_b64 s[4:5], -1, 0
	v_writelane_b32 v249, s4, 33
	s_cmp_eq_u32 s0, 8
	v_mov_b32_e32 v1, 0
	v_writelane_b32 v249, s5, 34
	s_cselect_b64 s[4:5], -1, 0
	v_writelane_b32 v249, s4, 35
	s_cmp_eq_u32 s0, 7
	s_mov_b32 s37, 0
	v_writelane_b32 v249, s5, 36
	s_cselect_b64 s[4:5], -1, 0
	v_writelane_b32 v249, s4, 37
	s_cmp_eq_u32 s0, 6
	v_lshlrev_b32_e32 v226, 2, v0
	v_writelane_b32 v249, s5, 38
	s_cselect_b64 s[4:5], -1, 0
	v_writelane_b32 v249, s4, 39
	s_cmp_eq_u32 s0, 5
	v_mov_b32_e32 v227, 1
	v_writelane_b32 v249, s5, 40
	s_cselect_b64 s[4:5], -1, 0
	v_writelane_b32 v249, s4, 41
	s_cmp_eq_u32 s0, 4
	v_mov_b32_e32 v228, 0x3ecc95a3
	v_writelane_b32 v249, s5, 42
	s_cselect_b64 s[4:5], -1, 0
	v_writelane_b32 v249, s4, 43
	s_cmp_eq_u32 s0, 3
	s_mov_b32 s35, 0x3d800000
	v_writelane_b32 v249, s5, 44
	s_cselect_b64 s[4:5], -1, 0
	v_writelane_b32 v249, s4, 45
	s_cmp_eq_u32 s0, 2
	v_mov_b32_e32 v229, 0x3c088889
	v_writelane_b32 v249, s5, 46
	s_cselect_b64 s[4:5], -1, 0
	v_writelane_b32 v249, s4, 47
	s_cmp_eq_u32 s0, 1
	v_mov_b32_e32 v230, 0x358637bd
	v_writelane_b32 v249, s5, 48
	s_cselect_b64 s[4:5], -1, 0
	v_writelane_b32 v249, s4, 49
	s_cmp_eq_u32 s0, 0
	v_mov_b32_e32 v231, 0x3727c5ac
	v_writelane_b32 v249, s5, 50
	s_cselect_b64 s[4:5], -1, 0
	s_lshl_b32 s0, s0, 8
	s_add_u32 s0, s80, s0
	v_writelane_b32 v249, s4, 51
	s_addc_u32 s1, s81, 0
	v_mov_b32_e32 v232, 0x260
	v_writelane_b32 v249, s5, 52
	s_add_u32 s4, s0, 0x1400
	s_addc_u32 s5, s1, 0
	v_writelane_b32 v249, s4, 53
	s_add_u32 s0, s0, 0x2400
	s_addc_u32 s1, s1, 0
	v_writelane_b32 v249, s5, 54
	v_writelane_b32 v249, s0, 55
	v_mov_b32_e32 v233, 0x1200
	v_mov_b32_e32 v234, 0xe00
	v_writelane_b32 v249, s1, 56
	s_add_u32 s0, s80, 0x3400
	s_addc_u32 s1, s81, 0
	v_writelane_b32 v249, s0, 57
	v_mov_b32_e32 v235, 0x7f800000
	v_mov_b32_e32 v242, v1
	v_writelane_b32 v249, s1, 58
	s_add_u32 s0, s80, 0x3500
	s_addc_u32 s1, s81, 0
	v_writelane_b32 v249, s0, 59
	v_mov_b32_e32 v243, v1
	v_mov_b32_e32 v236, 2
	v_writelane_b32 v249, s1, 60
	s_and_b32 s0, s2, 31
	s_cmp_lg_u32 s0, 0
	s_cselect_b64 s[0:1], -1, 0
	v_writelane_b32 v249, s0, 61
	s_lshl_b64 s[70:71], s[2:3], 17
	s_lshl_b64 s[22:23], s[2:3], 2
	v_writelane_b32 v249, s1, 62
	s_lshl_b64 s[0:1], s[2:3], 16
	v_writelane_b32 v249, s0, 63
	v_mov_b32_e32 v237, 0x400
	s_movk_i32 s90, 0x1400
	v_writelane_b32 v248, s1, 0
	s_lshl_b64 s[0:1], s[2:3], 8
	v_writelane_b32 v248, s0, 1
	s_mov_b32 s91, 0x10000
	s_mov_b32 s86, 0x18000
	v_writelane_b32 v248, s1, 2
	s_lshl_b64 s[0:1], s[2:3], 13
	v_writelane_b32 v248, s0, 3
	s_mov_b32 s87, 0x8000
	s_mov_b32 s33, 0xbfb8aa3b
	v_writelane_b32 v248, s1, 4
	s_lshl_b32 s0, s2, 9
	v_writelane_b32 v248, s0, 5
	s_lshl_b64 s[0:1], s[2:3], 10
	v_writelane_b32 v248, s0, 6
	s_movk_i32 s72, 0x44
	s_movk_i32 s74, 0x220
	v_writelane_b32 v248, s1, 7
	s_lshl_b64 s[0:1], s[2:3], 15
	v_writelane_b32 v248, s0, 8
	s_mov_b32 s93, 0x5040100
	s_mov_b32 s94, 0x7060302
	v_writelane_b32 v248, s1, 9
	s_mul_hi_i32 s0, s2, 0xffff1000
	v_writelane_b32 v248, s0, 10
	s_mul_i32 s0, s2, 0xffff1000
	v_writelane_b32 v248, s0, 11
	s_mul_hi_i32 s0, s2, 0xfffff100
	v_writelane_b32 v248, s0, 12
	s_mul_i32 s0, s2, 0xfffff100
	v_writelane_b32 v248, s0, 13
	v_readlane_b32 s0, v249, 6
	v_readlane_b32 s1, v249, 7
	s_add_u32 s0, s0, 0x6000080
	v_writelane_b32 v248, s0, 14
	s_addc_u32 s0, s1, 0
	v_writelane_b32 v248, s0, 15
	s_add_u32 s0, s88, 0xe140000
	s_addc_u32 s1, s89, 0
	v_writelane_b32 v248, s0, 16
	s_mov_b32 s95, 0xe001000
	s_mov_b32 s96, 0xe003000
	v_writelane_b32 v248, s1, 17
	s_add_u32 s0, s88, 0xe014000
	s_addc_u32 s1, s89, 0
	v_writelane_b32 v248, s0, 18
	s_mov_b32 s97, 0xf800000
	s_mov_b64 s[2:3], -1
	v_writelane_b32 v248, s1, 19
	s_add_u32 s0, s88, 0xe1c0080
	v_writelane_b32 v248, s0, 20
	s_addc_u32 s0, s89, 0
	v_writelane_b32 v248, s0, 21
	s_add_u32 s0, s88, 0xe140080
	v_writelane_b32 v248, s0, 22
	s_addc_u32 s0, s89, 0
	v_writelane_b32 v248, s0, 23
	s_add_u32 s0, s88, 0xe000080
	v_writelane_b32 v248, s0, 24
	s_addc_u32 s0, s89, 0
	v_writelane_b32 v248, s0, 25
	s_add_i32 s0, 0, 0x22000
	v_writelane_b32 v248, s0, 26
	s_add_i32 s0, 0, 0x22004
	v_writelane_b32 v248, s0, 27
	s_add_i32 s1, 0, 0x12800
	v_writelane_b32 v248, s1, 28
	v_writelane_b32 v248, s70, 29
	s_mov_b32 s0, 0xe002000
	s_add_i32 s92, 0, 0x13000
	s_add_i32 s73, 0, 0x12a00
	s_mov_b64 s[8:9], 0
	s_mov_b64 s[6:7], 0x80
	s_mov_b64 s[12:13], 0x14000
	s_mov_b64 s[28:29], 0x800
	s_mov_b64 s[30:31], 0x4000
	s_mov_b64 s[82:83], 0x50000
	s_mov_b64 s[14:15], 0x8000
	s_mov_b64 s[24:25], 0x40000
	s_mov_b64 s[16:17], 0x20000
	s_mov_b32 s18, s37
	v_writelane_b32 v248, s71, 30
	v_writelane_b32 v248, s73, 31
	s_branch .LBB0_120

; __device__ __forceinline__ float bflo(unsigned w) { return __uint_as_float(w << 16); }
; __device__ __forceinline__ float bfhi(unsigned w) { return __uint_as_float(w & 0xffff0000u); }
; __device__ __forceinline__ void ln_panel_b(bf16_t* hb, float* outf, const float* gam, const float* bet) {
;     ...
; #pragma unroll
;         for (int b = 0; b < NB; ++b)
; #pragma unroll
;             for (int j = 0; j < 2; ++j)
; #pragma unroll
;                 for (int k = 0; k < 4; ++k) { v[b][8 * j + 2 * k] = bflo(nxt[b][j][k]); v[b][8 * j + 2 * k + 1] = bfhi(nxt[b][j][k]); }
;         if (it + 1 < 32 / NB) {
; #pragma unroll
;             for (int b = 0; b < NB; ++b)
; #pragma unroll
;                 for (int j = 0; j < 2; ++j) nxt[b][j] = ((const u32x4*)(hb + (size_t)(r + NB + b) * DM))[lane + 64 * j];
;         }
;         float s[NB], s2[NB];
; #pragma unroll
;         for (int b = 0; b < NB; ++b) { s[b] = 0.f;
; #pragma unroll
;             for (int k = 0; k < 16; ++k) s[b] += v[b][k]; }
; #pragma unroll
;         for (int o = 1; o < 64; o <<= 1)
; #pragma unroll
;             for (int b = 0; b < NB; ++b) s[b] += __shfl_xor(s[b], o);
; #pragma unroll
;         for (int b = 0; b < NB; ++b) { const float mean = s[b] * (1.f / DM); s2[b] = 0.f;
; #pragma unroll
;             for (int k = 0; k < 16; ++k) { v[b][k] -= mean; s2[b] += v[b][k] * v[b][k]; } }
; #pragma unroll
;         for (int o = 1; o < 64; o <<= 1)
; #pragma unroll
;             for (int b = 0; b < NB; ++b) s2[b] += __shfl_xor(s2[b], o);
.LBB0_425:
	s_waitcnt vmcnt(0)
	v_lshlrev_b32_e32 v0, 16, v34
	v_and_b32_e32 v51, 0xffff0000, v34
	v_add_f32_e32 v86, 0, v0
	v_lshlrev_b32_e32 v56, 16, v35
	v_add_f32_e32 v86, v86, v51
	v_and_b32_e32 v57, 0xffff0000, v35
	v_add_f32_e32 v86, v86, v56
	v_lshlrev_b32_e32 v58, 16, v36
	v_add_f32_e32 v86, v86, v57
	v_and_b32_e32 v59, 0xffff0000, v36
	v_lshlrev_b32_e32 v70, 16, v42
	v_add_f32_e32 v86, v86, v58
	v_lshlrev_b32_e32 v60, 16, v37
	v_and_b32_e32 v71, 0xffff0000, v42
	v_add_f32_e32 v86, v86, v59
	v_add_f32_e32 v87, 0, v70
	v_and_b32_e32 v61, 0xffff0000, v37
	v_lshlrev_b32_e32 v72, 16, v43
	v_add_f32_e32 v86, v86, v60
	v_add_f32_e32 v87, v87, v71
	v_lshlrev_b32_e32 v62, 16, v38
	v_and_b32_e32 v73, 0xffff0000, v43
	v_add_f32_e32 v86, v86, v61
	v_add_f32_e32 v87, v87, v72
	v_and_b32_e32 v63, 0xffff0000, v38
	v_lshlrev_b32_e32 v74, 16, v44
	v_add_f32_e32 v86, v86, v62
	v_add_f32_e32 v87, v87, v73
	v_lshlrev_b32_e32 v64, 16, v39
	v_and_b32_e32 v75, 0xffff0000, v44
	v_add_f32_e32 v86, v86, v63
	v_add_f32_e32 v87, v87, v74
	v_and_b32_e32 v65, 0xffff0000, v39
	v_lshlrev_b32_e32 v76, 16, v45
	v_add_f32_e32 v86, v86, v64
	v_add_f32_e32 v87, v87, v75
	v_lshlrev_b32_e32 v66, 16, v40
	v_and_b32_e32 v77, 0xffff0000, v45
	v_add_f32_e32 v86, v86, v65
	v_add_f32_e32 v87, v87, v76
	v_and_b32_e32 v67, 0xffff0000, v40
	v_lshlrev_b32_e32 v78, 16, v46
	v_add_f32_e32 v86, v86, v66
	v_add_f32_e32 v87, v87, v77
	v_lshlrev_b32_e32 v68, 16, v41
	v_and_b32_e32 v79, 0xffff0000, v46
	v_add_f32_e32 v86, v86, v67
	v_add_f32_e32 v87, v87, v78
	v_and_b32_e32 v69, 0xffff0000, v41
	v_lshlrev_b32_e32 v80, 16, v47
	v_add_f32_e32 v86, v86, v68
	v_add_f32_e32 v87, v87, v79
	v_and_b32_e32 v81, 0xffff0000, v47
	v_add_f32_e32 v86, v86, v69
	v_add_f32_e32 v87, v87, v80
	v_lshlrev_b32_e32 v82, 16, v48
	v_add_f32_e32 v87, v87, v81
	ds_bpermute_b32 v88, v191, v86
	v_and_b32_e32 v83, 0xffff0000, v48
	v_add_f32_e32 v87, v87, v82
	v_lshlrev_b32_e32 v84, 16, v49
	v_add_f32_e32 v87, v87, v83
	v_and_b32_e32 v85, 0xffff0000, v49
	v_add_f32_e32 v87, v87, v84
	v_add_f32_e32 v87, v87, v85
	s_waitcnt lgkmcnt(0)
	v_add_f32_e32 v86, v86, v88
	ds_bpermute_b32 v88, v191, v87
	v_lshl_add_u64 v[54:55], v[52:53], 0, s[26:27]
	s_mov_b32 s1, 0x6001000
	v_add_co_u32_e32 v46, vcc, s1, v54
	s_waitcnt lgkmcnt(0)
	v_add_f32_e32 v87, v87, v88
	ds_bpermute_b32 v88, v218, v86
	v_addc_co_u32_e32 v47, vcc, 0, v55, vcc
	global_load_dwordx4 v[34:37], v[46:47], off
	global_load_dwordx4 v[38:41], v[46:47], off offset:1024
	global_load_dwordx4 v[42:45], v[46:47], off offset:2048
	s_nop 0
	global_load_dwordx4 v[46:49], v[46:47], off offset:3072
	s_mov_b32 s1, 0x6000000
	s_waitcnt lgkmcnt(0)
	v_add_f32_e32 v86, v86, v88
	ds_bpermute_b32 v88, v218, v87
	s_add_u32 s26, s26, 0x1000
	s_addc_u32 s27, s27, 0
	s_cmpk_lg_u32 s26, 0xf000
	s_waitcnt lgkmcnt(0)
	v_add_f32_e32 v87, v87, v88
	ds_bpermute_b32 v88, v219, v86
	s_waitcnt lgkmcnt(0)
	v_add_f32_e32 v86, v86, v88
	ds_bpermute_b32 v88, v219, v87
	s_waitcnt lgkmcnt(0)
	v_add_f32_e32 v87, v87, v88
	ds_bpermute_b32 v88, v220, v86
	s_waitcnt lgkmcnt(0)
	v_add_f32_e32 v86, v86, v88
	ds_bpermute_b32 v88, v220, v87
	s_waitcnt lgkmcnt(0)
	v_add_f32_e32 v87, v87, v88
	ds_bpermute_b32 v88, v221, v86
	s_waitcnt lgkmcnt(0)
	v_add_f32_e32 v86, v86, v88
	ds_bpermute_b32 v88, v221, v87
	s_waitcnt lgkmcnt(0)
	v_add_f32_e32 v87, v87, v88
	ds_bpermute_b32 v88, v222, v86
	s_waitcnt lgkmcnt(0)
	v_add_f32_e32 v86, v86, v88
	ds_bpermute_b32 v88, v222, v87
	v_fmac_f32_e32 v51, 0xba800000, v86
	v_fmac_f32_e32 v0, 0xba800000, v86
	v_fmac_f32_e32 v56, 0xba800000, v86
	v_fmac_f32_e32 v57, 0xba800000, v86
	s_waitcnt lgkmcnt(0)
	v_add_f32_e32 v87, v87, v88
	v_mul_f32_e32 v88, v51, v51
	v_fmac_f32_e32 v88, v0, v0
	v_fmac_f32_e32 v88, v56, v56
	v_fmac_f32_e32 v88, v57, v57
	v_fmac_f32_e32 v58, 0xba800000, v86
	v_fmac_f32_e32 v88, v58, v58
	v_fmac_f32_e32 v59, 0xba800000, v86
	v_fmac_f32_e32 v71, 0xba800000, v87
	v_fmac_f32_e32 v88, v59, v59
	v_fmac_f32_e32 v60, 0xba800000, v86
	v_fmac_f32_e32 v61, 0xba800000, v86
	v_fmac_f32_e32 v62, 0xba800000, v86
	v_fmac_f32_e32 v63, 0xba800000, v86
	v_fmac_f32_e32 v64, 0xba800000, v86
	v_fmac_f32_e32 v65, 0xba800000, v86
	v_fmac_f32_e32 v66, 0xba800000, v86
	v_fmac_f32_e32 v67, 0xba800000, v86
	v_fmac_f32_e32 v68, 0xba800000, v86
	v_fmac_f32_e32 v69, 0xba800000, v86
	v_fmac_f32_e32 v70, 0xba800000, v87
	v_mul_f32_e32 v86, v71, v71
	v_fmac_f32_e32 v88, v60, v60
	v_fmac_f32_e32 v86, v70, v70
	v_fmac_f32_e32 v72, 0xba800000, v87
	v_fmac_f32_e32 v88, v61, v61
	v_fmac_f32_e32 v86, v72, v72
	v_fmac_f32_e32 v73, 0xba800000, v87
	v_fmac_f32_e32 v88, v62, v62
	v_fmac_f32_e32 v86, v73, v73
	v_fmac_f32_e32 v74, 0xba800000, v87
	v_fmac_f32_e32 v88, v63, v63
	v_fmac_f32_e32 v86, v74, v74
	v_fmac_f32_e32 v75, 0xba800000, v87
	v_fmac_f32_e32 v88, v64, v64
	v_fmac_f32_e32 v86, v75, v75
	v_fmac_f32_e32 v76, 0xba800000, v87
	v_fmac_f32_e32 v88, v65, v65
	v_fmac_f32_e32 v86, v76, v76
	v_fmac_f32_e32 v77, 0xba800000, v87
	v_fmac_f32_e32 v88, v66, v66
	v_fmac_f32_e32 v86, v77, v77
	v_fmac_f32_e32 v78, 0xba800000, v87
	v_fmac_f32_e32 v88, v67, v67
	v_fmac_f32_e32 v86, v78, v78
	v_fmac_f32_e32 v79, 0xba800000, v87
	v_fmac_f32_e32 v88, v68, v68
	v_fmac_f32_e32 v86, v79, v79
	v_fmac_f32_e32 v80, 0xba800000, v87
	v_fmac_f32_e32 v88, v69, v69
	v_fmac_f32_e32 v86, v80, v80
	v_fmac_f32_e32 v81, 0xba800000, v87
	v_fmac_f32_e32 v86, v81, v81
	v_fmac_f32_e32 v82, 0xba800000, v87
	v_fmac_f32_e32 v83, 0xba800000, v87
	v_fmac_f32_e32 v84, 0xba800000, v87
	v_fmac_f32_e32 v85, 0xba800000, v87
	ds_bpermute_b32 v87, v191, v88
	v_fmac_f32_e32 v86, v82, v82
	v_fmac_f32_e32 v86, v83, v83
	v_fmac_f32_e32 v86, v84, v84
	v_fmac_f32_e32 v86, v85, v85
	s_waitcnt lgkmcnt(0)
; __device__ __forceinline__ unsigned pk2(float lo, float hi) { unsigned r; asm("v_cvt_pk_bf16_f32 %0, %1, %2" : "=v"(r) : "v"(lo), "v"(hi)); return r; }
; __device__ __forceinline__ void ln_panel_b(bf16_t* hb, float* outf, const float* gam, const float* bet) {
;     ...
;             for (int b = 0; b < NB; ++b) s2[b] += __shfl_xor(s2[b], o);
; #pragma unroll
;         for (int b = 0; b < NB; ++b) {
;             const float rstd = 1.f / sqrtf(s2[b] * (1.f / DM) + LN_EPS);
; #pragma unroll
;             for (int j = 0; j < 2; ++j) {
;                 float o[8];
; #pragma unroll
;                 for (int k = 0; k < 8; ++k) o[k] = v[b][8 * j + k] * rstd * gv[j][k >> 2][k & 3] + bv[j][k >> 2][k & 3];
;                 if (outf) { f32x4* op = (f32x4*)(outf + (size_t)(r + b) * DM + 512 * j + 8 * lane); op[0] = (f32x4){o[0], o[1], o[2], o[3]}; op[1] = (f32x4){o[4], o[5], o[6], o[7]}; }
;                 else { u32x4 w; w.x = pk2(o[0], o[1]); w.y = pk2(o[2], o[3]); w.z = pk2(o[4], o[5]); w.w = pk2(o[6], o[7]); ((u32x4*)(hb + (size_t)(r + b) * DM))[lane + 64 * j] = w; }
;             }
	v_add_f32_e32 v87, v88, v87
	ds_bpermute_b32 v88, v191, v86
	s_waitcnt lgkmcnt(0)
	v_add_f32_e32 v86, v86, v88
	ds_bpermute_b32 v88, v218, v87
	s_waitcnt lgkmcnt(0)
	v_add_f32_e32 v87, v87, v88
	ds_bpermute_b32 v88, v218, v86
	s_waitcnt lgkmcnt(0)
	v_add_f32_e32 v86, v86, v88
	ds_bpermute_b32 v88, v219, v87
	s_waitcnt lgkmcnt(0)
	v_add_f32_e32 v87, v87, v88
	ds_bpermute_b32 v88, v219, v86
	s_waitcnt lgkmcnt(0)
	v_add_f32_e32 v86, v86, v88
	ds_bpermute_b32 v88, v220, v87
	s_waitcnt lgkmcnt(0)
	v_add_f32_e32 v87, v87, v88
	ds_bpermute_b32 v88, v220, v86
	s_waitcnt lgkmcnt(0)
	v_add_f32_e32 v86, v86, v88
	ds_bpermute_b32 v88, v221, v87
	s_waitcnt lgkmcnt(0)
	v_add_f32_e32 v87, v87, v88
	ds_bpermute_b32 v88, v221, v86
	s_waitcnt lgkmcnt(0)
	v_add_f32_e32 v86, v86, v88
	ds_bpermute_b32 v88, v222, v87
	s_waitcnt lgkmcnt(0)
	v_add_f32_e32 v87, v87, v88
	ds_bpermute_b32 v88, v222, v86
	v_fmamk_f32 v87, v87, 0x3a800000, v231
	v_cmp_gt_f32_e32 vcc, s97, v87
	s_waitcnt lgkmcnt(0)
	v_add_f32_e32 v86, v86, v88
	v_mul_f32_e32 v88, 0x4f800000, v87
	v_cndmask_b32_e32 v87, v87, v88, vcc
	v_sqrt_f32_e32 v88, v87
	s_nop 0
	v_add_u32_e32 v89, -1, v88
	v_fma_f32 v90, -v89, v88, v87
	v_cmp_ge_f32_e64 s[2:3], 0, v90
	v_add_u32_e32 v90, 1, v88
	s_nop 0
	v_cndmask_b32_e64 v89, v88, v89, s[2:3]
	v_fma_f32 v88, -v90, v88, v87
	v_cmp_lt_f32_e64 s[2:3], 0, v88
	s_nop 1
	v_cndmask_b32_e64 v88, v89, v90, s[2:3]
	v_mul_f32_e32 v89, 0x37800000, v88
	v_cndmask_b32_e32 v88, v88, v89, vcc
	v_cmp_class_f32_e32 vcc, v87, v232
	s_nop 1
	v_cndmask_b32_e32 v87, v88, v87, vcc
	v_div_scale_f32 v88, s[2:3], v87, v87, 1.0
	v_rcp_f32_e32 v89, v88
	s_nop 0
	v_fma_f32 v90, -v88, v89, 1.0
	v_fmac_f32_e32 v89, v90, v89
	v_div_scale_f32 v90, vcc, 1.0, v87, 1.0
	v_mul_f32_e32 v91, v90, v89
	v_fma_f32 v92, -v88, v91, v90
	v_fmac_f32_e32 v91, v92, v89
	v_fma_f32 v88, -v88, v91, v90
	v_div_fmas_f32 v88, v88, v89, v91
	v_div_fixup_f32 v87, v88, v87, 1.0
	v_mul_f32_e32 v56, v56, v87
	v_fma_f32 v88, v32, v56, v24
	v_mul_f32_e32 v56, v57, v87
	v_fma_f32 v57, v33, v56, v25
	v_mul_f32_e32 v56, v58, v87
	v_fma_f32 v58, v26, v56, v18
	v_mul_f32_e32 v56, v59, v87
	v_fma_f32 v59, v27, v56, v19
	v_mul_f32_e32 v56, v60, v87
	v_fma_f32 v60, v28, v56, v20
	v_mul_f32_e32 v56, v61, v87
	v_mul_f32_e32 v0, v0, v87
	v_mul_f32_e32 v51, v51, v87
	v_fma_f32 v61, v29, v56, v21
	v_cvt_pk_bf16_f32 v58, v58, v59
	v_cvt_pk_bf16_f32 v59, v60, v61
	v_add_co_u32_e32 v60, vcc, s1, v54
	v_mul_f32_e32 v54, v64, v87
	v_fma_f32 v0, v30, v0, v22
	v_fma_f32 v51, v31, v51, v23
	v_cvt_pk_bf16_f32 v56, v0, v51
	v_addc_co_u32_e32 v61, vcc, 0, v55, vcc
	v_fma_f32 v55, v16, v54, v8
	v_mul_f32_e32 v54, v65, v87
	v_cvt_pk_bf16_f32 v57, v88, v57
	global_store_dwordx4 v[60:61], v[56:59], off
	v_mul_f32_e32 v0, v62, v87
	v_fma_f32 v0, v14, v0, v6
	v_fma_f32 v56, v17, v54, v9
	v_mul_f32_e32 v54, v66, v87
	v_fma_f32 v57, v10, v54, v2
	v_mul_f32_e32 v54, v67, v87
	v_fma_f32 v58, v11, v54, v3
	v_mul_f32_e32 v54, v68, v87
	v_mul_f32_e32 v51, v63, v87
	v_fma_f32 v59, v12, v54, v4
	v_mul_f32_e32 v54, v69, v87
	v_fma_f32 v51, v15, v51, v7
	v_fma_f32 v62, v13, v54, v5
	v_cvt_pk_bf16_f32 v54, v0, v51
	v_fmamk_f32 v0, v86, 0x3a800000, v231
	v_cmp_gt_f32_e32 vcc, s97, v0
	v_mul_f32_e32 v51, 0x4f800000, v0
	v_cvt_pk_bf16_f32 v55, v55, v56
	v_cvt_pk_bf16_f32 v56, v57, v58
	v_cvt_pk_bf16_f32 v57, v59, v62
	global_store_dwordx4 v[60:61], v[54:57], off offset:1024
	v_cndmask_b32_e32 v0, v0, v51, vcc
	v_sqrt_f32_e32 v51, v0
	s_nop 0
	v_add_u32_e32 v54, -1, v51
	v_fma_f32 v55, -v54, v51, v0
	v_cmp_ge_f32_e64 s[2:3], 0, v55
	v_add_u32_e32 v55, 1, v51
	s_nop 0
	v_cndmask_b32_e64 v54, v51, v54, s[2:3]
	v_fma_f32 v51, -v55, v51, v0
	v_cmp_lt_f32_e64 s[2:3], 0, v51
	s_nop 1
	v_cndmask_b32_e64 v51, v54, v55, s[2:3]
	v_mul_f32_e32 v54, 0x37800000, v51
	v_cndmask_b32_e32 v51, v51, v54, vcc
	v_cmp_class_f32_e32 vcc, v0, v232
	s_nop 1
	v_cndmask_b32_e32 v0, v51, v0, vcc
	v_div_scale_f32 v51, s[2:3], v0, v0, 1.0
	v_rcp_f32_e32 v54, v51
	s_nop 0
	v_fma_f32 v55, -v51, v54, 1.0
	v_fmac_f32_e32 v54, v55, v54
	v_div_scale_f32 v55, vcc, 1.0, v0, 1.0
	v_mul_f32_e32 v56, v55, v54
	v_fma_f32 v57, -v51, v56, v55
	v_fmac_f32_e32 v56, v57, v54
	v_fma_f32 v51, -v51, v56, v55
	v_div_fmas_f32 v51, v51, v54, v56
	v_div_fixup_f32 v0, v51, v0, 1.0
	v_mul_f32_e32 v54, v71, v0
	v_mul_f32_e32 v55, v72, v0
	v_mul_f32_e32 v56, v73, v0
	v_mul_f32_e32 v57, v74, v0
	v_mul_f32_e32 v51, v70, v0
	v_fma_f32 v54, v31, v54, v23
	v_fma_f32 v55, v32, v55, v24
	v_fma_f32 v56, v33, v56, v25
	v_fma_f32 v57, v26, v57, v18
	v_mul_f32_e32 v58, v75, v0
	v_mul_f32_e32 v59, v76, v0
	v_mul_f32_e32 v62, v77, v0
	v_fma_f32 v51, v30, v51, v22
	v_fma_f32 v58, v27, v58, v19
	v_fma_f32 v59, v28, v59, v20
	v_fma_f32 v62, v29, v62, v21
	v_cvt_pk_bf16_f32 v54, v51, v54
	v_cvt_pk_bf16_f32 v55, v55, v56
	v_cvt_pk_bf16_f32 v56, v57, v58
	v_cvt_pk_bf16_f32 v57, v59, v62
	global_store_dwordx4 v[60:61], v[54:57], off offset:2048
	v_mul_f32_e32 v51, v78, v0
	v_mul_f32_e32 v58, v83, v0
	v_mul_f32_e32 v54, v79, v0
	v_mul_f32_e32 v55, v80, v0
	v_mul_f32_e32 v56, v81, v0
	v_mul_f32_e32 v57, v82, v0
	v_fma_f32 v54, v15, v54, v7
	v_fma_f32 v55, v16, v55, v8
	v_fma_f32 v56, v17, v56, v9
	v_fma_f32 v57, v10, v57, v2
	v_mul_f32_e32 v59, v84, v0
	v_mul_f32_e32 v0, v85, v0
	v_fma_f32 v51, v14, v51, v6
	v_fma_f32 v58, v11, v58, v3
	v_fma_f32 v59, v12, v59, v4
	v_fma_f32 v0, v13, v0, v5
	v_cvt_pk_bf16_f32 v54, v51, v54
	v_cvt_pk_bf16_f32 v55, v55, v56
	v_cvt_pk_bf16_f32 v56, v57, v58
	v_cvt_pk_bf16_f32 v57, v59, v0
	global_store_dwordx4 v[60:61], v[54:57], off offset:3072
	s_cbranch_scc1 .LBB0_425
; __device__ __forceinline__ float bflo(unsigned w) { return __uint_as_float(w << 16); }
; __device__ __forceinline__ float bfhi(unsigned w) { return __uint_as_float(w & 0xffff0000u); }
; __device__ __forceinline__ void ln_panel_b(bf16_t* hb, float* outf, const float* gam, const float* bet) {
;     ...
; #pragma unroll
;         for (int b = 0; b < NB; ++b)
; #pragma unroll
;             for (int j = 0; j < 2; ++j)
; #pragma unroll
;                 for (int k = 0; k < 4; ++k) { v[b][8 * j + 2 * k] = bflo(nxt[b][j][k]); v[b][8 * j + 2 * k + 1] = bfhi(nxt[b][j][k]); }
;         if (it + 1 < 32 / NB) {
; #pragma unroll
;             for (int b = 0; b < NB; ++b)
; #pragma unroll
;                 for (int j = 0; j < 2; ++j) nxt[b][j] = ((const u32x4*)(hb + (size_t)(r + NB + b) * DM))[lane + 64 * j];
;         }
;         float s[NB], s2[NB];
; #pragma unroll
;         for (int b = 0; b < NB; ++b) { s[b] = 0.f;
; #pragma unroll
;             for (int k = 0; k < 16; ++k) s[b] += v[b][k]; }
; #pragma unroll
;         for (int o = 1; o < 64; o <<= 1)
; #pragma unroll
;             for (int b = 0; b < NB; ++b) s[b] += __shfl_xor(s[b], o);
; #pragma unroll
;         for (int b = 0; b < NB; ++b) { const float mean = s[b] * (1.f / DM); s2[b] = 0.f;
; #pragma unroll
;             for (int k = 0; k < 16; ++k) { v[b][k] -= mean; s2[b] += v[b][k] * v[b][k]; } }
; #pragma unroll
;         for (int o = 1; o < 64; o <<= 1)
; #pragma unroll
;             for (int b = 0; b < NB; ++b) s2[b] += __shfl_xor(s2[b], o);
	s_waitcnt vmcnt(7)
	v_and_b32_e32 v65, 0xffff0000, v34
	v_lshlrev_b32_e32 v34, 16, v34
	v_add_f32_e32 v66, 0, v34
	v_and_b32_e32 v64, 0xffff0000, v35
	v_lshlrev_b32_e32 v35, 16, v35
	v_add_f32_e32 v66, v66, v65
	v_add_f32_e32 v66, v66, v35
	v_and_b32_e32 v63, 0xffff0000, v36
	v_lshlrev_b32_e32 v36, 16, v36
	v_add_f32_e32 v66, v66, v64
	s_waitcnt vmcnt(5)
	v_and_b32_e32 v57, 0xffff0000, v42
	v_lshlrev_b32_e32 v42, 16, v42
	v_add_f32_e32 v66, v66, v36
	v_and_b32_e32 v62, 0xffff0000, v37
	v_lshlrev_b32_e32 v37, 16, v37
	v_add_f32_e32 v66, v66, v63
	v_add_f32_e32 v67, 0, v42
	v_and_b32_e32 v56, 0xffff0000, v43
	v_lshlrev_b32_e32 v43, 16, v43
	v_add_f32_e32 v66, v66, v37
	v_add_f32_e32 v67, v67, v57
	v_and_b32_e32 v61, 0xffff0000, v38
	v_lshlrev_b32_e32 v38, 16, v38
	v_add_f32_e32 v66, v66, v62
	v_add_f32_e32 v67, v67, v43
	v_and_b32_e32 v55, 0xffff0000, v44
	v_lshlrev_b32_e32 v44, 16, v44
	v_add_f32_e32 v66, v66, v38
	v_add_f32_e32 v67, v67, v56
	v_and_b32_e32 v60, 0xffff0000, v39
	v_lshlrev_b32_e32 v39, 16, v39
	v_add_f32_e32 v66, v66, v61
	v_add_f32_e32 v67, v67, v44
	v_and_b32_e32 v54, 0xffff0000, v45
	v_lshlrev_b32_e32 v45, 16, v45
	v_add_f32_e32 v66, v66, v39
	v_add_f32_e32 v67, v67, v55
	v_and_b32_e32 v59, 0xffff0000, v40
	v_lshlrev_b32_e32 v40, 16, v40
	v_add_f32_e32 v66, v66, v60
	v_add_f32_e32 v67, v67, v45
	s_waitcnt vmcnt(4)
	v_and_b32_e32 v53, 0xffff0000, v46
	v_lshlrev_b32_e32 v46, 16, v46
	v_add_f32_e32 v66, v66, v40
	v_add_f32_e32 v67, v67, v54
	v_and_b32_e32 v58, 0xffff0000, v41
	v_lshlrev_b32_e32 v41, 16, v41
	v_add_f32_e32 v66, v66, v59
	v_add_f32_e32 v67, v67, v46
	v_and_b32_e32 v52, 0xffff0000, v47
	v_lshlrev_b32_e32 v47, 16, v47
	v_add_f32_e32 v66, v66, v41
	v_add_f32_e32 v67, v67, v53
	v_add_f32_e32 v66, v66, v58
	v_add_f32_e32 v67, v67, v47
	v_and_b32_e32 v51, 0xffff0000, v48
	v_lshlrev_b32_e32 v48, 16, v48
	v_add_f32_e32 v67, v67, v52
	ds_bpermute_b32 v68, v191, v66
	v_add_f32_e32 v67, v67, v48
	v_and_b32_e32 v0, 0xffff0000, v49
	v_lshlrev_b32_e32 v49, 16, v49
	v_add_f32_e32 v67, v67, v51
	v_add_f32_e32 v67, v67, v49
	v_add_f32_e32 v67, v67, v0
	s_waitcnt lgkmcnt(0)
	v_add_f32_e32 v66, v66, v68
	ds_bpermute_b32 v68, v191, v67
	s_or_b32 s10, s10, 30
	s_ashr_i32 s11, s10, 31
	v_lshlrev_b32_e32 v50, 4, v50
	s_movk_i32 s42, 0x400
	s_waitcnt lgkmcnt(0)
	v_add_f32_e32 v67, v67, v68
	ds_bpermute_b32 v68, v218, v66
	v_mov_b32_e32 v131, v1
	v_mov_b32_e32 v135, v1
	v_mov_b32_e32 v133, v1
	s_waitcnt lgkmcnt(0)
	v_add_f32_e32 v66, v66, v68
	ds_bpermute_b32 v68, v218, v67
	s_waitcnt lgkmcnt(0)
	v_add_f32_e32 v67, v67, v68
	ds_bpermute_b32 v68, v219, v66
	s_waitcnt lgkmcnt(0)
	v_add_f32_e32 v66, v66, v68
	ds_bpermute_b32 v68, v219, v67
	s_waitcnt lgkmcnt(0)
	v_add_f32_e32 v67, v67, v68
	ds_bpermute_b32 v68, v220, v66
	s_waitcnt lgkmcnt(0)
	v_add_f32_e32 v66, v66, v68
	ds_bpermute_b32 v68, v220, v67
	s_waitcnt lgkmcnt(0)
	v_add_f32_e32 v67, v67, v68
	ds_bpermute_b32 v68, v221, v66
	s_waitcnt lgkmcnt(0)
	v_add_f32_e32 v66, v66, v68
	ds_bpermute_b32 v68, v221, v67
	s_waitcnt lgkmcnt(0)
	v_add_f32_e32 v67, v67, v68
	ds_bpermute_b32 v68, v222, v66
	s_waitcnt lgkmcnt(0)
	v_add_f32_e32 v66, v66, v68
	ds_bpermute_b32 v68, v222, v67
	v_fmac_f32_e32 v65, 0xba800000, v66
	v_fmac_f32_e32 v34, 0xba800000, v66
	v_fmac_f32_e32 v35, 0xba800000, v66
	v_fmac_f32_e32 v64, 0xba800000, v66
	s_waitcnt lgkmcnt(0)
	v_add_f32_e32 v67, v67, v68
	v_mul_f32_e32 v68, v65, v65
	v_fmac_f32_e32 v68, v34, v34
	v_fmac_f32_e32 v68, v35, v35
	v_fmac_f32_e32 v68, v64, v64
	v_fmac_f32_e32 v36, 0xba800000, v66
	v_fmac_f32_e32 v68, v36, v36
	v_fmac_f32_e32 v63, 0xba800000, v66
	v_fmac_f32_e32 v57, 0xba800000, v67
	v_fmac_f32_e32 v68, v63, v63
	v_fmac_f32_e32 v37, 0xba800000, v66
	v_fmac_f32_e32 v62, 0xba800000, v66
	v_fmac_f32_e32 v38, 0xba800000, v66
	v_fmac_f32_e32 v61, 0xba800000, v66
	v_fmac_f32_e32 v39, 0xba800000, v66
	v_fmac_f32_e32 v60, 0xba800000, v66
	v_fmac_f32_e32 v40, 0xba800000, v66
	v_fmac_f32_e32 v59, 0xba800000, v66
	v_fmac_f32_e32 v41, 0xba800000, v66
	v_fmac_f32_e32 v58, 0xba800000, v66
	v_fmac_f32_e32 v42, 0xba800000, v67
	v_mul_f32_e32 v66, v57, v57
	v_fmac_f32_e32 v68, v37, v37
	v_fmac_f32_e32 v66, v42, v42
	v_fmac_f32_e32 v43, 0xba800000, v67
	v_fmac_f32_e32 v68, v62, v62
	v_fmac_f32_e32 v66, v43, v43
	v_fmac_f32_e32 v56, 0xba800000, v67
	v_fmac_f32_e32 v68, v38, v38
	v_fmac_f32_e32 v66, v56, v56
	v_fmac_f32_e32 v44, 0xba800000, v67
	v_fmac_f32_e32 v68, v61, v61
	v_fmac_f32_e32 v66, v44, v44
	v_fmac_f32_e32 v55, 0xba800000, v67
	v_fmac_f32_e32 v68, v39, v39
	v_fmac_f32_e32 v66, v55, v55
	v_fmac_f32_e32 v45, 0xba800000, v67
	v_fmac_f32_e32 v68, v60, v60
	v_fmac_f32_e32 v66, v45, v45
	v_fmac_f32_e32 v54, 0xba800000, v67
	v_fmac_f32_e32 v68, v40, v40
	v_fmac_f32_e32 v66, v54, v54
	v_fmac_f32_e32 v46, 0xba800000, v67
	v_fmac_f32_e32 v68, v59, v59
	v_fmac_f32_e32 v66, v46, v46
	v_fmac_f32_e32 v53, 0xba800000, v67
	v_fmac_f32_e32 v68, v41, v41
	v_fmac_f32_e32 v66, v53, v53
	v_fmac_f32_e32 v47, 0xba800000, v67
	v_fmac_f32_e32 v68, v58, v58
	v_fmac_f32_e32 v66, v47, v47
	v_fmac_f32_e32 v52, 0xba800000, v67
	v_fmac_f32_e32 v66, v52, v52
	v_fmac_f32_e32 v48, 0xba800000, v67
	v_fmac_f32_e32 v51, 0xba800000, v67
	v_fmac_f32_e32 v49, 0xba800000, v67
	v_fmac_f32_e32 v0, 0xba800000, v67
	ds_bpermute_b32 v67, v191, v68
	v_fmac_f32_e32 v66, v48, v48
	v_fmac_f32_e32 v66, v51, v51
	v_fmac_f32_e32 v66, v49, v49
	v_fmac_f32_e32 v66, v0, v0
	s_waitcnt lgkmcnt(0)
	v_add_f32_e32 v67, v68, v67
	ds_bpermute_b32 v68, v191, v66
	s_waitcnt lgkmcnt(0)
	v_add_f32_e32 v66, v66, v68
	ds_bpermute_b32 v68, v218, v67
	s_waitcnt lgkmcnt(0)
; __device__ __forceinline__ unsigned pk2(float lo, float hi) { unsigned r; asm("v_cvt_pk_bf16_f32 %0, %1, %2" : "=v"(r) : "v"(lo), "v"(hi)); return r; }
; __device__ __forceinline__ void block_fence() { __builtin_amdgcn_fence(__ATOMIC_RELEASE, "workgroup"); __syncthreads(); __builtin_amdgcn_fence(__ATOMIC_ACQUIRE, "workgroup"); }
; __device__ __forceinline__ void ln_panel_b(bf16_t* hb, float* outf, const float* gam, const float* bet) {
;     ...
; #pragma unroll
;         for (int b = 0; b < NB; ++b) {
;             const float rstd = 1.f / sqrtf(s2[b] * (1.f / DM) + LN_EPS);
; #pragma unroll
;             for (int j = 0; j < 2; ++j) {
;                 float o[8];
; #pragma unroll
;                 for (int k = 0; k < 8; ++k) o[k] = v[b][8 * j + k] * rstd * gv[j][k >> 2][k & 3] + bv[j][k >> 2][k & 3];
;                 if (outf) { f32x4* op = (f32x4*)(outf + (size_t)(r + b) * DM + 512 * j + 8 * lane); op[0] = (f32x4){o[0], o[1], o[2], o[3]}; op[1] = (f32x4){o[4], o[5], o[6], o[7]}; }
;                 else { u32x4 w; w.x = pk2(o[0], o[1]); w.y = pk2(o[2], o[3]); w.z = pk2(o[4], o[5]); w.w = pk2(o[6], o[7]); ((u32x4*)(hb + (size_t)(r + b) * DM))[lane + 64 * j] = w; }
;             }
; __global__ void __launch_bounds__(512, 2) fwd_megakernel(Args a) {
;     ...
;         block_fence();
	v_add_f32_e32 v67, v67, v68
	ds_bpermute_b32 v68, v218, v66
	s_waitcnt lgkmcnt(0)
	v_add_f32_e32 v66, v66, v68
	ds_bpermute_b32 v68, v219, v67
	s_waitcnt lgkmcnt(0)
	v_add_f32_e32 v67, v67, v68
	ds_bpermute_b32 v68, v219, v66
	s_waitcnt lgkmcnt(0)
	v_add_f32_e32 v66, v66, v68
	ds_bpermute_b32 v68, v220, v67
	s_waitcnt lgkmcnt(0)
	v_add_f32_e32 v67, v67, v68
	ds_bpermute_b32 v68, v220, v66
	s_waitcnt lgkmcnt(0)
	v_add_f32_e32 v66, v66, v68
	ds_bpermute_b32 v68, v221, v67
	s_waitcnt lgkmcnt(0)
	v_add_f32_e32 v67, v67, v68
	ds_bpermute_b32 v68, v221, v66
	s_waitcnt lgkmcnt(0)
	v_add_f32_e32 v66, v66, v68
	ds_bpermute_b32 v68, v222, v67
	s_waitcnt lgkmcnt(0)
	v_add_f32_e32 v67, v67, v68
	ds_bpermute_b32 v68, v222, v66
	v_fmamk_f32 v67, v67, 0x3a800000, v231
	v_cmp_gt_f32_e32 vcc, s97, v67
	s_waitcnt lgkmcnt(0)
	v_add_f32_e32 v66, v66, v68
	v_mul_f32_e32 v68, 0x4f800000, v67
	v_cndmask_b32_e32 v67, v67, v68, vcc
	v_sqrt_f32_e32 v68, v67
	s_nop 0
	v_add_u32_e32 v69, -1, v68
	v_fma_f32 v70, -v69, v68, v67
	v_cmp_ge_f32_e64 s[2:3], 0, v70
	v_add_u32_e32 v70, 1, v68
	s_nop 0
	v_cndmask_b32_e64 v69, v68, v69, s[2:3]
	v_fma_f32 v68, -v70, v68, v67
	v_cmp_lt_f32_e64 s[2:3], 0, v68
	s_nop 1
	v_cndmask_b32_e64 v68, v69, v70, s[2:3]
	v_mul_f32_e32 v69, 0x37800000, v68
	v_cndmask_b32_e32 v68, v68, v69, vcc
	v_cmp_class_f32_e32 vcc, v67, v232
	s_nop 1
	v_cndmask_b32_e32 v67, v68, v67, vcc
	v_div_scale_f32 v68, s[2:3], v67, v67, 1.0
	v_rcp_f32_e32 v69, v68
	s_lshl_b64 s[2:3], s[10:11], 11
	s_add_u32 s2, s4, s2
	s_addc_u32 s3, s5, s3
	v_fma_f32 v70, -v68, v69, 1.0
	v_fmac_f32_e32 v69, v70, v69
	v_div_scale_f32 v70, vcc, 1.0, v67, 1.0
	v_mul_f32_e32 v71, v70, v69
	v_fma_f32 v72, -v68, v71, v70
	v_fmac_f32_e32 v71, v72, v69
	v_fma_f32 v68, -v68, v71, v70
	v_div_fmas_f32 v68, v68, v69, v71
	v_div_fixup_f32 v67, v68, v67, 1.0
	v_mul_f32_e32 v34, v34, v67
	v_fma_f32 v34, v30, v34, v22
	v_mul_f32_e32 v65, v65, v67
	v_mul_f32_e32 v35, v35, v67
	v_mul_f32_e32 v36, v36, v67
	v_mul_f32_e32 v37, v37, v67
	v_fma_f32 v65, v31, v65, v23
	v_fma_f32 v35, v32, v35, v24
	v_mul_f32_e32 v64, v64, v67
	v_fma_f32 v36, v26, v36, v18
	v_mul_f32_e32 v63, v63, v67
	v_fma_f32 v37, v28, v37, v20
	v_mul_f32_e32 v62, v62, v67
	v_cvt_pk_bf16_f32 v34, v34, v65
	v_fma_f32 v64, v33, v64, v25
	v_fma_f32 v63, v27, v63, v19
	v_fma_f32 v62, v29, v62, v21
	v_cvt_pk_bf16_f32 v35, v35, v64
	v_cvt_pk_bf16_f32 v36, v36, v63
	v_cvt_pk_bf16_f32 v37, v37, v62
	global_store_dwordx4 v50, v[34:37], s[2:3]
	s_nop 1
	v_mul_f32_e32 v34, v38, v67
	v_fma_f32 v34, v14, v34, v6
	v_mul_f32_e32 v35, v61, v67
	v_mul_f32_e32 v36, v39, v67
	v_mul_f32_e32 v37, v60, v67
	v_fma_f32 v35, v15, v35, v7
	v_fma_f32 v36, v16, v36, v8
	v_fma_f32 v37, v17, v37, v9
	v_mul_f32_e32 v38, v40, v67
	v_mul_f32_e32 v39, v59, v67
	v_mul_f32_e32 v40, v41, v67
	v_mul_f32_e32 v41, v58, v67
	v_cvt_pk_bf16_f32 v34, v34, v35
	v_fma_f32 v38, v10, v38, v2
	v_fma_f32 v39, v11, v39, v3
	v_fma_f32 v40, v12, v40, v4
	v_fma_f32 v41, v13, v41, v5
	v_cvt_pk_bf16_f32 v35, v36, v37
	v_cvt_pk_bf16_f32 v36, v38, v39
	v_cvt_pk_bf16_f32 v37, v40, v41
	global_store_dwordx4 v50, v[34:37], s[2:3] offset:1024
	s_nop 1
	v_fmamk_f32 v34, v66, 0x3a800000, v231
	v_cmp_gt_f32_e32 vcc, s97, v34
	v_mul_f32_e32 v35, 0x4f800000, v34
	s_nop 0
	v_cndmask_b32_e32 v34, v34, v35, vcc
	v_sqrt_f32_e32 v35, v34
	s_nop 0
	v_add_u32_e32 v36, -1, v35
	v_fma_f32 v37, -v36, v35, v34
	v_cmp_ge_f32_e64 s[2:3], 0, v37
	v_add_u32_e32 v37, 1, v35
	s_nop 0
	v_cndmask_b32_e64 v36, v35, v36, s[2:3]
	v_fma_f32 v35, -v37, v35, v34
	v_cmp_lt_f32_e64 s[2:3], 0, v35
	s_nop 1
	v_cndmask_b32_e64 v35, v36, v37, s[2:3]
	v_mul_f32_e32 v36, 0x37800000, v35
	v_cndmask_b32_e32 v35, v35, v36, vcc
	v_cmp_class_f32_e32 vcc, v34, v232
	s_nop 1
	v_cndmask_b32_e32 v34, v35, v34, vcc
	v_div_scale_f32 v35, s[2:3], v34, v34, 1.0
	v_rcp_f32_e32 v36, v35
	s_or_b32 s2, s8, 31
	s_ashr_i32 s3, s2, 31
	s_lshl_b64 s[2:3], s[2:3], 11
	v_fma_f32 v37, -v35, v36, 1.0
	v_fmac_f32_e32 v36, v37, v36
	v_div_scale_f32 v37, vcc, 1.0, v34, 1.0
	v_mul_f32_e32 v38, v37, v36
	v_fma_f32 v39, -v35, v38, v37
	v_fmac_f32_e32 v38, v39, v36
	v_fma_f32 v35, -v35, v38, v37
	v_div_fmas_f32 v35, v35, v36, v38
	v_div_fixup_f32 v34, v35, v34, 1.0
	v_mul_f32_e32 v35, v42, v34
	v_fma_f32 v22, v30, v35, v22
	v_mul_f32_e32 v30, v57, v34
	v_fma_f32 v23, v31, v30, v23
	v_mul_f32_e32 v30, v43, v34
	v_fma_f32 v24, v32, v30, v24
	v_mul_f32_e32 v30, v56, v34
	v_fmac_f32_e32 v25, v33, v30
	v_mul_f32_e32 v30, v44, v34
	v_fma_f32 v26, v26, v30, v18
	v_mul_f32_e32 v18, v55, v34
	v_fma_f32 v27, v27, v18, v19
	v_mul_f32_e32 v18, v45, v34
	s_add_u32 s2, s4, s2
	v_fma_f32 v28, v28, v18, v20
	v_mul_f32_e32 v18, v54, v34
	s_addc_u32 s3, s5, s3
	v_fmac_f32_e32 v21, v29, v18
	v_cvt_pk_bf16_f32 v18, v22, v23
	v_cvt_pk_bf16_f32 v19, v24, v25
	v_cvt_pk_bf16_f32 v20, v26, v27
	v_cvt_pk_bf16_f32 v21, v28, v21
	global_store_dwordx4 v50, v[18:21], s[2:3]
	v_mul_f32_e32 v0, v0, v34
	v_fmac_f32_e32 v5, v13, v0
	v_mul_f32_e32 v18, v46, v34
	v_fma_f32 v6, v14, v18, v6
	v_mul_f32_e32 v14, v53, v34
	v_fma_f32 v7, v15, v14, v7
	v_mul_f32_e32 v14, v47, v34
	v_fma_f32 v8, v16, v14, v8
	v_mul_f32_e32 v14, v52, v34
	v_fmac_f32_e32 v9, v17, v14
	v_mul_f32_e32 v14, v48, v34
	v_fma_f32 v10, v10, v14, v2
	v_mul_f32_e32 v2, v51, v34
	v_fma_f32 v11, v11, v2, v3
	v_mul_f32_e32 v2, v49, v34
	v_fma_f32 v12, v12, v2, v4
	v_cvt_pk_bf16_f32 v2, v6, v7
	v_cvt_pk_bf16_f32 v3, v8, v9
	v_cvt_pk_bf16_f32 v4, v10, v11
	v_cvt_pk_bf16_f32 v5, v12, v5
	global_store_dwordx4 v50, v[2:5], s[2:3] offset:1024
	v_readlane_b32 s2, v249, 0
	v_readlane_b32 s3, v249, 1
	v_mov_b32_e32 v15, v189
	s_waitcnt vmcnt(0)
	s_barrier
	v_readfirstlane_b32 s98, v189
	s_nop 3
	s_cmp_ge_u32 s98, 64
	s_cbranch_scc1 .Lgrp_bar0_done
	s_lshr_b32 s98, s88, 21
	s_and_b32 s99, s98, 7
	s_lshr_b32 s98, s98, 5
	s_lshl_b32 s98, s98, 3
	s_or_b32 s98, s98, s99
	s_lshl_b32 s98, s98, 5
	v_readlane_b32 s99, v248, 36
	s_nop 3
	s_lshl_b32 s99, s99, 4
	s_add_u32 s98, s98, s99
	s_add_u32 s98, s98, 14336
	v_mov_b32_e32 v2, s98
	v_mov_b32_e32 v3, 1
	s_mov_b64 s[100:101], exec
	s_mov_b64 exec, 1
	v_readlane_b32 s99, v248, 62
	s_nop 3
	s_cmp_eq_u32 s99, 1
	s_cbranch_scc1 .Lgrp_bar0_nowb
	buffer_wbl2 sc1
.Lgrp_bar0_nowb:
	s_waitcnt vmcnt(0)
	global_atomic_add v2, v3, s[80:81]
	s_mov_b32 s99, 0

; __device__ __forceinline__ void block_fence() { __builtin_amdgcn_fence(__ATOMIC_RELEASE, "workgroup"); __syncthreads(); __builtin_amdgcn_fence(__ATOMIC_ACQUIRE, "workgroup"); }
; __global__ void __launch_bounds__(512, 2) fwd_megakernel(Args a) {
;     ...
;         block_fence();
;         {
.LBB0_441:
	v_readlane_b32 s2, v249, 0
	v_readlane_b32 s3, v249, 1
	v_mov_b32_e32 v15, v189
	s_waitcnt vmcnt(0)
	s_barrier
	s_waitcnt vmcnt(0) lgkmcnt(0)
	s_barrier
	v_readfirstlane_b32 s98, v189
	s_nop 3
	s_cmp_ge_u32 s98, 64
	s_cbranch_scc1 .Lgrp_bar1_done
	s_lshr_b32 s98, s88, 21
	s_and_b32 s99, s98, 7
	s_lshr_b32 s98, s98, 5
	s_lshl_b32 s98, s98, 3
	s_or_b32 s98, s98, s99
	s_lshl_b32 s98, s98, 5
	v_readlane_b32 s99, v248, 36
	s_nop 3
	s_lshl_b32 s99, s99, 4
	s_add_u32 s98, s98, s99
	s_add_u32 s98, s98, 14340
	v_mov_b32_e32 v2, s98
	v_mov_b32_e32 v3, 1
	s_mov_b64 s[100:101], exec
	s_mov_b64 exec, 1
	v_readlane_b32 s99, v248, 62
	s_nop 3
	s_cmp_eq_u32 s99, 1
	s_cbranch_scc1 .Lgrp_bar1_nowb
	buffer_wbl2 sc1

; __device__ __forceinline__ void block_fence() { __builtin_amdgcn_fence(__ATOMIC_RELEASE, "workgroup"); __syncthreads(); __builtin_amdgcn_fence(__ATOMIC_ACQUIRE, "workgroup"); }
; __global__ void __launch_bounds__(512, 2) fwd_megakernel(Args a) {
;     ...
;         block_fence();
.LBB0_456:
	v_readlane_b32 s2, v249, 0
	v_readlane_b32 s3, v249, 1
	s_waitcnt vmcnt(0)
	s_barrier
	s_waitcnt lgkmcnt(0)
	s_barrier
	v_readfirstlane_b32 s98, v189
	s_nop 3
	s_cmp_ge_u32 s98, 64
	s_cbranch_scc1 .Lgrp_bar2_done
	s_lshr_b32 s98, s88, 21
	s_and_b32 s99, s98, 7
	s_lshr_b32 s98, s98, 5
	s_lshl_b32 s98, s98, 3
	s_or_b32 s98, s98, s99
	s_lshl_b32 s98, s98, 5
	v_readlane_b32 s99, v248, 36
	s_nop 3
	s_lshl_b32 s99, s99, 4
	s_add_u32 s98, s98, s99
	s_add_u32 s98, s98, 14344
	v_mov_b32_e32 v2, s98
	v_mov_b32_e32 v3, 1
	s_mov_b64 s[100:101], exec
	s_mov_b64 exec, 1
	v_readlane_b32 s99, v248, 62
	s_nop 3
	s_cmp_eq_u32 s99, 1
	s_cbranch_scc1 .Lgrp_bar2_nowb
	buffer_wbl2 sc1
